# v158 + waves 4-7 issue their six next-item row gathers in the beta segment (where they only wait), waves 0-3 keep them spread through the prep: halves the texture-address pressure during the prep
# speedup vs baseline: 1.0186x; 1.0096x over previous
.LBB0_865:
	s_andn2_b64 vcc, exec, s[8:9]
	s_cbranch_vccnz .LBB0_911
	v_writelane_b32 v254, s24, 44
	s_ashr_i32 s8, s18, 1
	s_lshl_b32 s12, s18, 3
	v_writelane_b32 v254, s25, 45
	s_and_b32 s20, s18, 3
	s_and_b32 s9, s8, -2
	s_lshl_b32 s17, s18, 5
	s_lshl_b32 s22, s18, 4
	v_writelane_b32 v254, s12, 46
	s_ashr_i32 s12, s12, 31
	v_writelane_b32 v254, s12, 47
	s_add_u32 s12, s36, 0x16600000
	s_addc_u32 s13, s37, 0
	v_writelane_b32 v254, s12, 48
	v_lshrrev_b32_e32 v2, 4, v114
	v_and_b32_e32 v28, 15, v1
	v_writelane_b32 v254, s13, 49
	s_add_u32 s12, s36, 0x32380000
	v_writelane_b32 v254, s12, 50
	s_addc_u32 s12, s37, 0
	v_writelane_b32 v254, s12, 51
	s_add_u32 s12, s36, 0x3a780000
	s_addc_u32 s13, s37, 0
	v_writelane_b32 v254, s12, 52
	v_lshlrev_b32_e32 v32, 2, v2
	v_lshlrev_b32_e32 v34, 3, v2
	v_writelane_b32 v254, s13, 53
	s_add_u32 s12, s36, 0x18700000
	s_addc_u32 s13, s37, 0
	v_writelane_b32 v254, s12, 54
	v_lshl_or_b32 v43, s8, 4, v28
	v_mul_lo_u32 v44, v43, s76
	v_writelane_b32 v254, s13, 55
	s_add_u32 s12, s36, 0x36580000
	v_writelane_b32 v254, s12, 56
	s_addc_u32 s12, s37, 0
	v_writelane_b32 v254, s12, 57
	s_add_u32 s12, s36, 0x29f80000
	v_writelane_b32 v254, s12, 58
	s_addc_u32 s12, s37, 0
	s_cmp_le_i32 s9, s20
	s_cselect_b64 s[28:29], -1, 0
	s_or_b32 s21, s8, 1
	v_writelane_b32 v254, s12, 59
	s_cmp_le_i32 s21, s20
	s_cselect_b64 s[24:25], -1, 0
	s_lshl_b32 s12, s20, 4
	s_lshl_b32 s19, s20, 5
	v_readlane_b32 s26, v254, 32
	v_or_b32_e32 v30, s12, v28
	v_or_b32_e32 v33, s12, v32
	s_add_i32 s12, s26, s19
	v_add_u32_e32 v119, s12, v34
	v_readlane_b32 s12, v254, 33
	v_readlane_b32 s34, v254, 37
	s_add_i32 s23, 0, 0x12000
	v_mov_b32_e32 v35, s12
	v_readlane_b32 s12, v254, 34
	s_waitcnt vmcnt(0)
	v_mad_u32_u24 v120, v30, s76, v35
	v_mul_u32_u24_e32 v31, 0x90, v30
	v_mov_b32_e32 v35, s12
	v_readlane_b32 s12, v254, 35
	v_mad_u32_u24 v122, v30, s76, v35
	v_readlane_b32 s27, v254, 36
	v_mov_b32_e32 v35, s12
	s_add_i32 s12, s34, s19
	v_add_u32_e32 v129, s12, v34
	s_and_b32 s12, s18, 2
	s_cmp_eq_u32 s9, s12
	s_cselect_b64 s[40:41], -1, 0
	s_cmp_lt_i32 s18, 2
	v_add3_u32 v118, s23, v31, v34
	v_add3_u32 v126, s27, v31, v34
	v_bfe_u32 v31, v1, 2, 2
	s_cselect_b64 s[42:43], -1, 0
	s_cmp_eq_u32 s18, 0
	v_mad_u32_u24 v124, v30, s76, v35
	v_or_b32_e32 v35, v34, v31
	s_cselect_b32 s12, 16, 48
	s_cselect_b32 s13, 0, 64
	v_or3_b32 v31, s17, v31, v34
	v_mul_lo_u32 v31, v31, s76
	s_add_i32 s16, s13, 0
	v_or_b32_e32 v39, s12, v28
	s_lshl_b32 s12, s18, 6
	v_add_u32_e32 v31, s16, v31
	s_add_i32 s16, s12, s23
	v_mov_b32_e32 v40, s16
	v_mad_u32_u24 v40, v39, s76, v40
	v_mad_u32_u24 v39, v39, s76, 0
	s_cmp_lt_i32 s18, 4
	v_add_u32_e32 v41, s13, v39
	v_add_u32_e32 v39, s12, v39
	s_cselect_b64 s[12:13], -1, 0
	s_and_b32 s16, s17, 32
	v_add_u32_e32 v44, 0x1200, v44
	v_mad_u32_u24 v35, v35, s76, 0
	v_add_u32_e32 v130, 0, v44
	s_cmp_gt_u32 s20, 1
	v_lshlrev_b32_e32 v36, 3, v1
	v_writelane_b32 v254, s17, 60
	v_add_u32_e32 v42, s16, v35
	v_add_u32_e32 v45, s23, v44
	v_add_u32_e32 v44, s16, v130
	s_cselect_b64 s[16:17], -1, 0
	s_add_i32 s8, s23, s19
	v_mad_u32_u24 v116, v30, s76, 0
	v_and_b32_e32 v36, 24, v36
	v_add_u32_e32 v132, s8, v34
	s_add_i32 s8, s27, s19
	v_and_b32_e32 v117, 48, v1
	v_add_u32_e32 v128, v35, v36
	v_or_b32_e32 v37, s19, v34
	v_add_u32_e32 v38, s19, v116
	v_add_u32_e32 v133, s8, v34
	v_add_u32_e32 v35, s19, v35
	v_readlane_b32 s19, v254, 38
	s_lshl_b32 s8, s20, 6
	v_lshlrev_b32_e32 v1, 1, v1
	s_add_i32 s8, s19, s8
	v_and_b32_e32 v46, 48, v114
	v_and_b32_e32 v1, 0x60, v1
	v_add_u32_e32 v135, s8, v46
	s_and_b32 s8, s18, 0xffffffc
	v_lshl_or_b32 v1, s20, 3, v1
	v_or_b32_e32 v46, s8, v2
	v_add_u32_e32 v136, s26, v1
	v_add_u32_e32 v137, 0, v1
	v_lshrrev_b32_e32 v1, 3, v0
	s_mov_b32 s8, 0xffffff0
	v_and_or_b32 v1, v1, s8, v28
	s_lshl_b32 s8, s9, 4
	s_lshl_b32 s30, s9, 5
	v_bfe_u32 v47, v0, 6, 1
	v_lshlrev_b32_e32 v104, 4, v0
	v_or_b32_e32 v0, s8, v28
	v_or_b32_e32 v48, 2, v33
	v_or_b32_e32 v49, 3, v33
	s_cmp_lg_u32 s9, s20
	v_lshl_add_u32 v134, v30, 2, s19
	v_mul_lo_u32 v140, v0, s76
	v_cmp_lt_i32_e64 s[44:45], v0, v33
	v_cmp_gt_i32_e64 s[46:47], v0, v33
	v_cmp_lt_i32_e64 s[18:19], v0, v48
	v_cmp_lt_i32_e64 s[62:63], v0, v49
	v_or_b32_e32 v0, s8, v32
	s_cselect_b64 s[64:65], -1, 0
	s_lshl_b32 s8, s21, 4
	v_or_b32_e32 v50, 1, v0
	v_cmp_eq_u32_e32 vcc, v0, v30
	v_or_b32_e32 v28, s8, v28
	v_cmp_lt_i32_e64 s[52:53], v50, v30
	v_cndmask_b32_e64 v106, 0, 1.0, vcc
	v_cmp_eq_u32_e32 vcc, v50, v30
	v_or_b32_e32 v50, 3, v0
	v_cmp_lt_i32_e64 s[70:71], v28, v48
	v_cndmask_b32_e64 v107, 0, 1.0, vcc
	v_or_b32_e32 v51, 2, v0
	v_cmp_eq_u32_e32 vcc, v50, v30
	v_writelane_b32 v254, s70, 61
	v_cmp_lt_i32_e64 s[66:67], v28, v33
	v_cndmask_b32_e64 v109, 0, 1.0, vcc
	v_cmp_eq_u32_e32 vcc, v51, v30
	v_cmp_gt_i32_e64 s[68:69], v28, v33
	v_writelane_b32 v254, s71, 62
	v_cmp_lt_i32_e64 s[70:71], v28, v49
	v_mul_lo_u32 v141, v28, s76
	v_or_b32_e32 v28, s8, v32
	v_cndmask_b32_e64 v108, 0, 1.0, vcc
	v_or_b32_e32 v32, 1, v28
	v_cmp_eq_u32_e32 vcc, v28, v30
	v_or_b32_e32 v43, 16, v43
	v_cmp_lt_i32_e64 s[74:75], v32, v30
	v_cndmask_b32_e64 v110, 0, 1.0, vcc
	v_cmp_eq_u32_e32 vcc, v32, v30
	v_or_b32_e32 v32, 3, v28
	v_lshlrev_b32_e32 v2, 5, v2
	v_mul_lo_u32 v1, v1, s76
	v_mul_lo_u32 v43, v43, s76
	v_writelane_b32 v254, s70, 63
	s_lshl_b32 s31, s21, 5
	v_cndmask_b32_e64 v111, 0, 1.0, vcc
	v_or_b32_e32 v33, 2, v28
	v_cmp_eq_u32_e32 vcc, v32, v30
	v_mad_u32_u24 v29, v114, s76, 0
	v_mad_u32_u24 v37, v30, s76, v37
	v_lshlrev_b32_e32 v46, 4, v46
	v_lshl_or_b32 v138, v47, 4, v2
	v_add_u32_e32 v139, 0, v1
	v_lshl_or_b32 v2, v47, 6, v117
	v_add_u32_e32 v1, s26, v1
	v_add_u32_e32 v47, 0, v140
	v_add_u32_e32 v43, 0, v43
	v_cmp_lt_i32_e64 s[48:49], v0, v30
	v_cmp_gt_i32_e64 s[50:51], v0, v30
	v_cmp_lt_i32_e64 s[54:55], v51, v30
	v_cmp_gt_i32_e64 s[56:57], v51, v30
	v_cmp_lt_i32_e64 s[58:59], v50, v30
	v_cmp_gt_i32_e64 s[60:61], v50, v30
	v_writelane_b32 v255, s71, 0
	v_cmp_lt_i32_e64 s[70:71], v28, v30
	v_cmp_gt_i32_e64 s[72:73], v28, v30
	v_cndmask_b32_e64 v113, 0, 1.0, vcc
	v_cmp_eq_u32_e32 vcc, v33, v30
	v_cmp_lt_i32_e64 s[76:77], v33, v30
	s_cmp_lg_u32 s21, s20
	v_cmp_gt_i32_e64 s[78:79], v33, v30
	v_add_u32_e32 v33, s23, v140
	v_add_u32_e32 v48, s23, v141
	v_add_u32_e32 v49, s34, v140
	v_add_u32_e32 v50, s34, v141
	v_add_u32_e32 v51, s27, v140
	v_lshlrev_b32_e32 v0, 1, v0
	v_add_u32_e32 v52, s27, v141
	v_lshlrev_b32_e32 v28, 1, v28
	v_cmp_ne_u32_e64 s[38:39], 63, v114
	v_xor_b32_e32 v115, 63, v114
	v_add_u32_e32 v121, v120, v34
	v_add_u32_e32 v123, v122, v34
	v_add_u32_e32 v125, v124, v34
	v_add_u32_e32 v127, v116, v34
	v_add_u32_e32 v131, s34, v117
	v_ashrrev_i32_e32 v105, 31, v104
	v_cndmask_b32_e64 v112, 0, 1.0, vcc
	s_cselect_b64 s[20:21], -1, 0
	v_add_u32_e32 v142, s22, v29
	s_lshl_b32 s26, s90, 6
	v_add_u32_e32 v143, v47, v117
	v_add_u32_e32 v144, v43, v117
	v_add_u32_e32 v145, 0, v37
	v_add_u32_e32 v146, v38, v34
	v_add_u32_e32 v147, v31, v36
	v_add_u32_e32 v148, v40, v117
	v_add_u32_e32 v149, v41, v34
	v_add_u32_e32 v150, v39, v117
	v_add_u32_e32 v151, v45, v117
	v_add_u32_e32 v152, v49, v117
	v_add_u32_e32 v153, v50, v117
	v_add_u32_e32 v154, v35, v36
	v_add_u32_e32 v155, v51, v117
	v_add_u32_e32 v156, v33, v117
	v_add_u32_e32 v157, v116, v0
	v_add_u32_e32 v158, v52, v117
	v_add_u32_e32 v159, v48, v117
	v_add_u32_e32 v160, v116, v28
	v_add_u32_e32 v161, v139, v2
	v_add_u32_e32 v162, v1, v138
	v_add_u32_e32 v163, v42, v36
	v_add_u32_e32 v164, v44, v34
	v_add_u32_e32 v165, v116, v46
	s_sub_i32 s27, 0x82, s90
	v_cmp_lt_i32_e64 s[80:81], v32, v30
	v_cmp_gt_i32_e64 s[82:83], v32, v30
	v_add_u32_e32 v166, v116, v117
	v_add_u32_e32 v167, s30, v118
	v_add_u32_e32 v168, v119, v140
	v_add_u32_e32 v169, s30, v121
	v_add_u32_e32 v170, s30, v123
	v_add_u32_e32 v171, s30, v126
	v_add_u32_e32 v172, s30, v125
	v_add_u32_e32 v173, s30, v127
	v_add_u32_e32 v174, s31, v118
	v_add_u32_e32 v175, v119, v141
	v_add_u32_e32 v176, s31, v121
	v_add_u32_e32 v177, s31, v123
	v_add_u32_e32 v178, s31, v126
	v_add_u32_e32 v179, s31, v125
	v_add_u32_e32 v182, s31, v127
	v_add_u32_e32 v183, v120, v117
	v_add_u32_e32 v184, s30, v128
	v_add_u32_e32 v185, s31, v128
	v_add_u32_e32 v186, v129, v140
	v_add_u32_e32 v187, v129, v141
	v_add_u32_e32 v188, 0x14400, v145
	v_add_u32_e32 v189, 0x16800, v145
	v_add_u32_e32 v190, v130, v117
	v_add_u32_e32 v191, v131, v140
	v_add_u32_e32 v192, v131, v141
	v_add_u32_e32 v193, v132, v140
	v_add_u32_e32 v194, v133, v140
	v_add_u32_e32 v195, v132, v141
	v_add_u32_e32 v196, v133, v141
	v_add_u32_e32 v197, v124, v117
	v_add_u32_e32 v200, v122, v117
	v_add_u32_e32 v201, v137, v140
	v_add_u32_e32 v204, v136, v141
	v_add_u32_e32 v205, 8, v165
	v_add_u32_e32 v206, v137, v141
	v_add_u32_e32 v207, v139, v138
	v_mov_b32_e32 v212, 1.0
	v_mov_b32_e32 v213, 1.0
	v_mov_b32_e32 v214, 1.0
	v_mov_b32_e32 v215, 1.0
	v_mov_b32_e32 v216, 1.0
	v_mov_b32_e32 v217, 1.0
	v_mov_b32_e32 v218, 1.0
	v_mov_b32_e32 v219, 1.0
	v_readlane_b32 s101, v253, 10
	v_readlane_b32 s98, v253, 7
	v_readlane_b32 s99, v253, 0
	s_nop 3
	s_cmp_eq_u32 s98, 0x100
	s_cselect_b32 s98, 1, 0
	s_lshr_b32 s30, s99, 2
	s_mul_i32 s31, s30, 0x84
	s_add_i32 s99, s31, 4
	s_mov_b32 s31, 0x20000
	s_bitcmp1_b32 s30, 0
	s_cselect_b32 s30, 0xfffe0000, s31
	s_cselect_b32 s31, -1, 0
.LBB0_867:
	s_waitcnt vmcnt(4)
	s_add_i32 s91, s90, 1
	s_cmp_ge_i32 s91, s88
	s_cselect_b64 s[22:23], -1, 0
	s_cmp_lg_u32 s91, s99
	s_cselect_b32 s32, s98, 0
	s_andn2_b32 s32, s32, s22
	s_cmp_lg_u32 s32, 0
	s_cbranch_scc0 .Lf1_prep_slow
	s_cmp_ge_u32 s101, 4
	s_cbranch_scc1 .Lf1_prep_slow
	v_cvt_f32_f16 v28, v24
	v_lshrrev_b32_e32 v0, 16, v24
	v_cvt_f32_f16 v29, v0
	v_cvt_f32_f16 v30, v25
	v_lshrrev_b32_e32 v0, 16, v25
	v_cvt_f32_f16 v31, v0
	v_cvt_f32_f16 v32, v26
	v_lshrrev_b32_e32 v0, 16, v26
	v_cvt_f32_f16 v33, v0
	v_cvt_f32_f16 v34, v27
	v_lshrrev_b32_e32 v0, 16, v27
	v_cvt_f32_f16 v35, v0
	v_mul_f32_e32 v28, 0x3fb8aa3b, v28
	v_mul_f32_e32 v29, 0x3fb8aa3b, v29
	v_mul_f32_e32 v30, 0x3fb8aa3b, v30
	v_mul_f32_e32 v31, 0x3fb8aa3b, v31
	v_mul_f32_e32 v32, 0x3fb8aa3b, v32
	v_mul_f32_e32 v33, 0x3fb8aa3b, v33
	v_mul_f32_e32 v34, 0x3fb8aa3b, v34
	v_mul_f32_e32 v35, 0x3fb8aa3b, v35
	v_lshl_add_u64 v[230:231], v[230:231], 0, s[30:31]
	global_load_dwordx4 v[24:27], v[230:231], off
	ds_write_b128 v142, v[12:15] offset:36864
	v_lshl_add_u64 v[224:225], v[224:225], 0, s[30:31]
	global_load_dwordx4 v[12:15], v[224:225], off
	v_add_f32_dpp v28, v28, v28 row_shr:1 row_mask:0xf bank_mask:0xf bound_ctrl:1
	v_lshlrev_b32_e32 v68, 16, v16
	v_add_f32_dpp v29, v29, v29 row_shr:1 row_mask:0xf bank_mask:0xf bound_ctrl:1
	v_and_b32_e32 v69, 0xffff0000, v16
	v_add_f32_dpp v30, v30, v30 row_shr:1 row_mask:0xf bank_mask:0xf bound_ctrl:1
	v_lshlrev_b32_e32 v70, 16, v17
	v_add_f32_dpp v31, v31, v31 row_shr:1 row_mask:0xf bank_mask:0xf bound_ctrl:1
	v_and_b32_e32 v71, 0xffff0000, v17
	v_add_f32_dpp v32, v32, v32 row_shr:1 row_mask:0xf bank_mask:0xf bound_ctrl:1
	v_lshlrev_b32_e32 v72, 16, v18
	v_add_f32_dpp v33, v33, v33 row_shr:1 row_mask:0xf bank_mask:0xf bound_ctrl:1
	v_and_b32_e32 v73, 0xffff0000, v18
	v_add_f32_dpp v34, v34, v34 row_shr:1 row_mask:0xf bank_mask:0xf bound_ctrl:1
	v_lshlrev_b32_e32 v74, 16, v19
	v_add_f32_dpp v35, v35, v35 row_shr:1 row_mask:0xf bank_mask:0xf bound_ctrl:1
	v_and_b32_e32 v75, 0xffff0000, v19
	v_lshl_add_u64 v[226:227], v[226:227], 0, s[30:31]
	global_load_dwordx4 v[16:19], v[226:227], off
	v_add_f32_dpp v28, v28, v28 row_shr:2 row_mask:0xf bank_mask:0xf bound_ctrl:1
	v_lshlrev_b32_e32 v76, 16, v4
	v_add_f32_dpp v29, v29, v29 row_shr:2 row_mask:0xf bank_mask:0xf bound_ctrl:1
	v_and_b32_e32 v77, 0xffff0000, v4
	v_add_f32_dpp v30, v30, v30 row_shr:2 row_mask:0xf bank_mask:0xf bound_ctrl:1
	v_lshlrev_b32_e32 v78, 16, v5
	v_add_f32_dpp v31, v31, v31 row_shr:2 row_mask:0xf bank_mask:0xf bound_ctrl:1
	v_and_b32_e32 v79, 0xffff0000, v5
	v_add_f32_dpp v32, v32, v32 row_shr:2 row_mask:0xf bank_mask:0xf bound_ctrl:1
	v_lshlrev_b32_e32 v80, 16, v6
	v_add_f32_dpp v33, v33, v33 row_shr:2 row_mask:0xf bank_mask:0xf bound_ctrl:1
	v_and_b32_e32 v81, 0xffff0000, v6
	v_add_f32_dpp v34, v34, v34 row_shr:2 row_mask:0xf bank_mask:0xf bound_ctrl:1
	v_lshlrev_b32_e32 v82, 16, v7
	v_add_f32_dpp v35, v35, v35 row_shr:2 row_mask:0xf bank_mask:0xf bound_ctrl:1
	v_and_b32_e32 v83, 0xffff0000, v7
	v_lshl_add_u64 v[220:221], v[220:221], 0, s[30:31]
	global_load_dwordx4 v[4:7], v[220:221], off
	v_add_f32_dpp v28, v28, v28 row_shr:4 row_mask:0xf bank_mask:0xf bound_ctrl:1
	v_lshlrev_b32_e32 v84, 16, v20
	v_add_f32_dpp v29, v29, v29 row_shr:4 row_mask:0xf bank_mask:0xf bound_ctrl:1
	v_and_b32_e32 v85, 0xffff0000, v20
	v_add_f32_dpp v30, v30, v30 row_shr:4 row_mask:0xf bank_mask:0xf bound_ctrl:1
	v_lshlrev_b32_e32 v86, 16, v21
	v_add_f32_dpp v31, v31, v31 row_shr:4 row_mask:0xf bank_mask:0xf bound_ctrl:1
	v_and_b32_e32 v87, 0xffff0000, v21
	v_add_f32_dpp v32, v32, v32 row_shr:4 row_mask:0xf bank_mask:0xf bound_ctrl:1
	v_lshlrev_b32_e32 v88, 16, v22
	v_add_f32_dpp v33, v33, v33 row_shr:4 row_mask:0xf bank_mask:0xf bound_ctrl:1
	v_and_b32_e32 v89, 0xffff0000, v22
	v_add_f32_dpp v34, v34, v34 row_shr:4 row_mask:0xf bank_mask:0xf bound_ctrl:1
	v_lshlrev_b32_e32 v90, 16, v23
	v_add_f32_dpp v35, v35, v35 row_shr:4 row_mask:0xf bank_mask:0xf bound_ctrl:1
	v_and_b32_e32 v91, 0xffff0000, v23
	v_lshl_add_u64 v[228:229], v[228:229], 0, s[30:31]
	global_load_dwordx4 v[20:23], v[228:229], off
	v_add_f32_dpp v28, v28, v28 row_shr:8 row_mask:0xf bank_mask:0xf bound_ctrl:1
	v_lshlrev_b32_e32 v92, 16, v8
	v_add_f32_dpp v29, v29, v29 row_shr:8 row_mask:0xf bank_mask:0xf bound_ctrl:1
	v_and_b32_e32 v93, 0xffff0000, v8
	v_add_f32_dpp v30, v30, v30 row_shr:8 row_mask:0xf bank_mask:0xf bound_ctrl:1
	v_lshlrev_b32_e32 v94, 16, v9
	v_add_f32_dpp v31, v31, v31 row_shr:8 row_mask:0xf bank_mask:0xf bound_ctrl:1
	v_and_b32_e32 v95, 0xffff0000, v9
	v_add_f32_dpp v32, v32, v32 row_shr:8 row_mask:0xf bank_mask:0xf bound_ctrl:1
	v_lshlrev_b32_e32 v96, 16, v10
	v_add_f32_dpp v33, v33, v33 row_shr:8 row_mask:0xf bank_mask:0xf bound_ctrl:1
	v_and_b32_e32 v97, 0xffff0000, v10
	v_add_f32_dpp v34, v34, v34 row_shr:8 row_mask:0xf bank_mask:0xf bound_ctrl:1
	v_lshlrev_b32_e32 v98, 16, v11
	v_add_f32_dpp v35, v35, v35 row_shr:8 row_mask:0xf bank_mask:0xf bound_ctrl:1
	v_and_b32_e32 v99, 0xffff0000, v11
	v_lshl_add_u64 v[222:223], v[222:223], 0, s[30:31]
	global_load_dwordx4 v[8:11], v[222:223], off
	v_add_f32_dpp v28, v28, v28 row_bcast:15 row_mask:0xa bank_mask:0xf
	v_add_f32_dpp v29, v29, v29 row_bcast:15 row_mask:0xa bank_mask:0xf
	v_add_f32_dpp v30, v30, v30 row_bcast:15 row_mask:0xa bank_mask:0xf
	v_add_f32_dpp v31, v31, v31 row_bcast:15 row_mask:0xa bank_mask:0xf
	v_add_f32_dpp v32, v32, v32 row_bcast:15 row_mask:0xa bank_mask:0xf
	v_add_f32_dpp v33, v33, v33 row_bcast:15 row_mask:0xa bank_mask:0xf
	v_add_f32_dpp v34, v34, v34 row_bcast:15 row_mask:0xa bank_mask:0xf
	v_add_f32_dpp v35, v35, v35 row_bcast:15 row_mask:0xa bank_mask:0xf
	v_add_f32_dpp v28, v28, v28 row_bcast:31 row_mask:0xc bank_mask:0xf
	v_add_f32_dpp v29, v29, v29 row_bcast:31 row_mask:0xc bank_mask:0xf
	v_add_f32_dpp v30, v30, v30 row_bcast:31 row_mask:0xc bank_mask:0xf
	v_add_f32_dpp v31, v31, v31 row_bcast:31 row_mask:0xc bank_mask:0xf
	v_add_f32_dpp v32, v32, v32 row_bcast:31 row_mask:0xc bank_mask:0xf
	v_add_f32_dpp v33, v33, v33 row_bcast:31 row_mask:0xc bank_mask:0xf
	v_add_f32_dpp v34, v34, v34 row_bcast:31 row_mask:0xc bank_mask:0xf
	v_add_f32_dpp v35, v35, v35 row_bcast:31 row_mask:0xc bank_mask:0xf
	v_exp_f32_e32 v36, v28
	v_exp_f32_e32 v37, v29
	v_exp_f32_e32 v38, v30
	v_exp_f32_e32 v39, v31
	v_exp_f32_e32 v40, v32
	v_exp_f32_e32 v41, v33
	v_exp_f32_e32 v42, v34
	v_exp_f32_e32 v43, v35
	v_exp_f32_e64 v44, -v28
	v_exp_f32_e64 v45, -v29
	v_exp_f32_e64 v46, -v30
	v_exp_f32_e64 v47, -v31
	v_exp_f32_e64 v48, -v32
	v_exp_f32_e64 v49, -v33
	v_exp_f32_e64 v50, -v34
	v_exp_f32_e64 v51, -v35
	v_mov_b32_dpp v212, v36 wave_shr:1 row_mask:0xf bank_mask:0xf
	v_mov_b32_dpp v213, v37 wave_shr:1 row_mask:0xf bank_mask:0xf
	v_mov_b32_dpp v214, v38 wave_shr:1 row_mask:0xf bank_mask:0xf
	v_mov_b32_dpp v215, v39 wave_shr:1 row_mask:0xf bank_mask:0xf
	v_mov_b32_dpp v216, v40 wave_shr:1 row_mask:0xf bank_mask:0xf
	v_mov_b32_dpp v217, v41 wave_shr:1 row_mask:0xf bank_mask:0xf
	v_mov_b32_dpp v218, v42 wave_shr:1 row_mask:0xf bank_mask:0xf
	v_mov_b32_dpp v219, v43 wave_shr:1 row_mask:0xf bank_mask:0xf
	v_readlane_b32 s9, v254, 60
	s_add_i32 s9, s9, 0x21c00
	v_mov_b32_e32 v0, s9
	s_mov_b64 s[84:85], exec
	s_andn2_b64 exec, exec, s[38:39]
	ds_write_b128 v0, v[36:39]
	ds_write_b128 v0, v[40:43] offset:16
	s_mov_b64 exec, s[84:85]
	v_pk_mul_f32 v[68:69], v[212:213], v[68:69] neg_lo:[0,1] neg_hi:[0,1]
	v_pk_mul_f32 v[70:71], v[214:215], v[70:71] neg_lo:[0,1] neg_hi:[0,1]
	v_pk_mul_f32 v[72:73], v[216:217], v[72:73] neg_lo:[0,1] neg_hi:[0,1]
	v_pk_mul_f32 v[74:75], v[218:219], v[74:75] neg_lo:[0,1] neg_hi:[0,1]
	v_pk_mul_f32 v[76:77], v[36:37], v[76:77]
	v_pk_mul_f32 v[78:79], v[38:39], v[78:79]
	v_pk_mul_f32 v[80:81], v[40:41], v[80:81]
	v_pk_mul_f32 v[82:83], v[42:43], v[82:83]
	v_pk_mul_f32 v[84:85], v[44:45], v[84:85]
	v_pk_mul_f32 v[86:87], v[46:47], v[86:87]
	v_pk_mul_f32 v[88:89], v[48:49], v[88:89]
	v_pk_mul_f32 v[90:91], v[50:51], v[90:91]
	v_pk_mul_f32 v[92:93], v[44:45], v[92:93]
	v_pk_mul_f32 v[94:95], v[46:47], v[94:95]
	v_pk_mul_f32 v[96:97], v[48:49], v[96:97]
	v_pk_mul_f32 v[98:99], v[50:51], v[98:99]
	v_cvt_pk_bf16_f32 v52, v68, v69
	v_cvt_pk_bf16_f32 v53, v70, v71
	v_cvt_pk_bf16_f32 v54, v72, v73
	v_cvt_pk_bf16_f32 v55, v74, v75
	v_cvt_pk_bf16_f32 v56, v76, v77
	v_cvt_pk_bf16_f32 v57, v78, v79
	v_cvt_pk_bf16_f32 v58, v80, v81
	v_cvt_pk_bf16_f32 v59, v82, v83
	ds_write_b128 v142, v[52:55]
	ds_write_b128 v142, v[56:59] offset:27648
	v_cvt_pk_bf16_f32 v60, v84, v85
	v_cvt_pk_bf16_f32 v61, v86, v87
	v_cvt_pk_bf16_f32 v62, v88, v89
	v_cvt_pk_bf16_f32 v63, v90, v91
	v_cvt_pk_bf16_f32 v64, v92, v93
	v_cvt_pk_bf16_f32 v65, v94, v95
	v_cvt_pk_bf16_f32 v66, v96, v97
	v_cvt_pk_bf16_f32 v67, v98, v99
	ds_write_b128 v142, v[60:63] offset:9216
	ds_write_b128 v142, v[64:67] offset:18432
	s_branch .LBB0_877
.Lf1_prep_slow:
	v_cvt_f32_f16 v28, v24
	v_lshrrev_b32_e32 v0, 16, v24
	v_cvt_f32_f16 v29, v0
	v_cvt_f32_f16 v30, v25
	v_lshrrev_b32_e32 v0, 16, v25
	v_cvt_f32_f16 v31, v0
	v_cvt_f32_f16 v32, v26
	v_lshrrev_b32_e32 v0, 16, v26
	v_cvt_f32_f16 v33, v0
	v_cvt_f32_f16 v34, v27
	v_lshrrev_b32_e32 v0, 16, v27
	v_cvt_f32_f16 v35, v0
	v_mul_f32_e32 v28, 0x3fb8aa3b, v28
	v_mul_f32_e32 v29, 0x3fb8aa3b, v29
	v_mul_f32_e32 v30, 0x3fb8aa3b, v30
	v_mul_f32_e32 v31, 0x3fb8aa3b, v31
	v_mul_f32_e32 v32, 0x3fb8aa3b, v32
	v_mul_f32_e32 v33, 0x3fb8aa3b, v33
	v_mul_f32_e32 v34, 0x3fb8aa3b, v34
	v_mul_f32_e32 v35, 0x3fb8aa3b, v35
	ds_write_b128 v142, v[12:15] offset:36864
	v_add_f32_dpp v28, v28, v28 row_shr:1 row_mask:0xf bank_mask:0xf bound_ctrl:1
	v_lshlrev_b32_e32 v68, 16, v16
	v_add_f32_dpp v29, v29, v29 row_shr:1 row_mask:0xf bank_mask:0xf bound_ctrl:1
	v_and_b32_e32 v69, 0xffff0000, v16
	v_add_f32_dpp v30, v30, v30 row_shr:1 row_mask:0xf bank_mask:0xf bound_ctrl:1
	v_lshlrev_b32_e32 v70, 16, v17
	v_add_f32_dpp v31, v31, v31 row_shr:1 row_mask:0xf bank_mask:0xf bound_ctrl:1
	v_and_b32_e32 v71, 0xffff0000, v17
	v_add_f32_dpp v32, v32, v32 row_shr:1 row_mask:0xf bank_mask:0xf bound_ctrl:1
	v_lshlrev_b32_e32 v72, 16, v18
	v_add_f32_dpp v33, v33, v33 row_shr:1 row_mask:0xf bank_mask:0xf bound_ctrl:1
	v_and_b32_e32 v73, 0xffff0000, v18
	v_add_f32_dpp v34, v34, v34 row_shr:1 row_mask:0xf bank_mask:0xf bound_ctrl:1
	v_lshlrev_b32_e32 v74, 16, v19
	v_add_f32_dpp v35, v35, v35 row_shr:1 row_mask:0xf bank_mask:0xf bound_ctrl:1
	v_and_b32_e32 v75, 0xffff0000, v19
	v_add_f32_dpp v28, v28, v28 row_shr:2 row_mask:0xf bank_mask:0xf bound_ctrl:1
	v_lshlrev_b32_e32 v76, 16, v4
	v_add_f32_dpp v29, v29, v29 row_shr:2 row_mask:0xf bank_mask:0xf bound_ctrl:1
	v_and_b32_e32 v77, 0xffff0000, v4
	v_add_f32_dpp v30, v30, v30 row_shr:2 row_mask:0xf bank_mask:0xf bound_ctrl:1
	v_lshlrev_b32_e32 v78, 16, v5
	v_add_f32_dpp v31, v31, v31 row_shr:2 row_mask:0xf bank_mask:0xf bound_ctrl:1
	v_and_b32_e32 v79, 0xffff0000, v5
	v_add_f32_dpp v32, v32, v32 row_shr:2 row_mask:0xf bank_mask:0xf bound_ctrl:1
	v_lshlrev_b32_e32 v80, 16, v6
	v_add_f32_dpp v33, v33, v33 row_shr:2 row_mask:0xf bank_mask:0xf bound_ctrl:1
	v_and_b32_e32 v81, 0xffff0000, v6
	v_add_f32_dpp v34, v34, v34 row_shr:2 row_mask:0xf bank_mask:0xf bound_ctrl:1
	v_lshlrev_b32_e32 v82, 16, v7
	v_add_f32_dpp v35, v35, v35 row_shr:2 row_mask:0xf bank_mask:0xf bound_ctrl:1
	v_and_b32_e32 v83, 0xffff0000, v7
	v_add_f32_dpp v28, v28, v28 row_shr:4 row_mask:0xf bank_mask:0xf bound_ctrl:1
	v_lshlrev_b32_e32 v84, 16, v20
	v_add_f32_dpp v29, v29, v29 row_shr:4 row_mask:0xf bank_mask:0xf bound_ctrl:1
	v_and_b32_e32 v85, 0xffff0000, v20
	v_add_f32_dpp v30, v30, v30 row_shr:4 row_mask:0xf bank_mask:0xf bound_ctrl:1
	v_lshlrev_b32_e32 v86, 16, v21
	v_add_f32_dpp v31, v31, v31 row_shr:4 row_mask:0xf bank_mask:0xf bound_ctrl:1
	v_and_b32_e32 v87, 0xffff0000, v21
	v_add_f32_dpp v32, v32, v32 row_shr:4 row_mask:0xf bank_mask:0xf bound_ctrl:1
	v_lshlrev_b32_e32 v88, 16, v22
	v_add_f32_dpp v33, v33, v33 row_shr:4 row_mask:0xf bank_mask:0xf bound_ctrl:1
	v_and_b32_e32 v89, 0xffff0000, v22
	v_add_f32_dpp v34, v34, v34 row_shr:4 row_mask:0xf bank_mask:0xf bound_ctrl:1
	v_lshlrev_b32_e32 v90, 16, v23
	v_add_f32_dpp v35, v35, v35 row_shr:4 row_mask:0xf bank_mask:0xf bound_ctrl:1
	v_and_b32_e32 v91, 0xffff0000, v23
	v_add_f32_dpp v28, v28, v28 row_shr:8 row_mask:0xf bank_mask:0xf bound_ctrl:1
	v_lshlrev_b32_e32 v92, 16, v8
	v_add_f32_dpp v29, v29, v29 row_shr:8 row_mask:0xf bank_mask:0xf bound_ctrl:1
	v_and_b32_e32 v93, 0xffff0000, v8
	v_add_f32_dpp v30, v30, v30 row_shr:8 row_mask:0xf bank_mask:0xf bound_ctrl:1
	v_lshlrev_b32_e32 v94, 16, v9
	v_add_f32_dpp v31, v31, v31 row_shr:8 row_mask:0xf bank_mask:0xf bound_ctrl:1
	v_and_b32_e32 v95, 0xffff0000, v9
	v_add_f32_dpp v32, v32, v32 row_shr:8 row_mask:0xf bank_mask:0xf bound_ctrl:1
	v_lshlrev_b32_e32 v96, 16, v10
	v_add_f32_dpp v33, v33, v33 row_shr:8 row_mask:0xf bank_mask:0xf bound_ctrl:1
	v_and_b32_e32 v97, 0xffff0000, v10
	v_add_f32_dpp v34, v34, v34 row_shr:8 row_mask:0xf bank_mask:0xf bound_ctrl:1
	v_lshlrev_b32_e32 v98, 16, v11
	v_add_f32_dpp v35, v35, v35 row_shr:8 row_mask:0xf bank_mask:0xf bound_ctrl:1
	v_and_b32_e32 v99, 0xffff0000, v11
	v_add_f32_dpp v28, v28, v28 row_bcast:15 row_mask:0xa bank_mask:0xf
	v_add_f32_dpp v29, v29, v29 row_bcast:15 row_mask:0xa bank_mask:0xf
	v_add_f32_dpp v30, v30, v30 row_bcast:15 row_mask:0xa bank_mask:0xf
	v_add_f32_dpp v31, v31, v31 row_bcast:15 row_mask:0xa bank_mask:0xf
	v_add_f32_dpp v32, v32, v32 row_bcast:15 row_mask:0xa bank_mask:0xf
	v_add_f32_dpp v33, v33, v33 row_bcast:15 row_mask:0xa bank_mask:0xf
	v_add_f32_dpp v34, v34, v34 row_bcast:15 row_mask:0xa bank_mask:0xf
	v_add_f32_dpp v35, v35, v35 row_bcast:15 row_mask:0xa bank_mask:0xf
	v_add_f32_dpp v28, v28, v28 row_bcast:31 row_mask:0xc bank_mask:0xf
	v_add_f32_dpp v29, v29, v29 row_bcast:31 row_mask:0xc bank_mask:0xf
	v_add_f32_dpp v30, v30, v30 row_bcast:31 row_mask:0xc bank_mask:0xf
	v_add_f32_dpp v31, v31, v31 row_bcast:31 row_mask:0xc bank_mask:0xf
	v_add_f32_dpp v32, v32, v32 row_bcast:31 row_mask:0xc bank_mask:0xf
	v_add_f32_dpp v33, v33, v33 row_bcast:31 row_mask:0xc bank_mask:0xf
	v_add_f32_dpp v34, v34, v34 row_bcast:31 row_mask:0xc bank_mask:0xf
	v_add_f32_dpp v35, v35, v35 row_bcast:31 row_mask:0xc bank_mask:0xf
	v_exp_f32_e32 v36, v28
	v_exp_f32_e32 v37, v29
	v_exp_f32_e32 v38, v30
	v_exp_f32_e32 v39, v31
	v_exp_f32_e32 v40, v32
	v_exp_f32_e32 v41, v33
	v_exp_f32_e32 v42, v34
	v_exp_f32_e32 v43, v35
	v_exp_f32_e64 v44, -v28
	v_exp_f32_e64 v45, -v29
	v_exp_f32_e64 v46, -v30
	v_exp_f32_e64 v47, -v31
	v_exp_f32_e64 v48, -v32
	v_exp_f32_e64 v49, -v33
	v_exp_f32_e64 v50, -v34
	v_exp_f32_e64 v51, -v35
	v_mov_b32_dpp v212, v36 wave_shr:1 row_mask:0xf bank_mask:0xf
	v_mov_b32_dpp v213, v37 wave_shr:1 row_mask:0xf bank_mask:0xf
	v_mov_b32_dpp v214, v38 wave_shr:1 row_mask:0xf bank_mask:0xf
	v_mov_b32_dpp v215, v39 wave_shr:1 row_mask:0xf bank_mask:0xf
	v_mov_b32_dpp v216, v40 wave_shr:1 row_mask:0xf bank_mask:0xf
	v_mov_b32_dpp v217, v41 wave_shr:1 row_mask:0xf bank_mask:0xf
	v_mov_b32_dpp v218, v42 wave_shr:1 row_mask:0xf bank_mask:0xf
	v_mov_b32_dpp v219, v43 wave_shr:1 row_mask:0xf bank_mask:0xf
	v_readlane_b32 s9, v254, 60
	s_add_i32 s9, s9, 0x21c00
	v_mov_b32_e32 v0, s9
	s_mov_b64 s[84:85], exec
	s_andn2_b64 exec, exec, s[38:39]
	ds_write_b128 v0, v[36:39]
	ds_write_b128 v0, v[40:43] offset:16
	s_mov_b64 exec, s[84:85]
	v_pk_mul_f32 v[68:69], v[212:213], v[68:69] neg_lo:[0,1] neg_hi:[0,1]
	v_pk_mul_f32 v[70:71], v[214:215], v[70:71] neg_lo:[0,1] neg_hi:[0,1]
	v_pk_mul_f32 v[72:73], v[216:217], v[72:73] neg_lo:[0,1] neg_hi:[0,1]
	v_pk_mul_f32 v[74:75], v[218:219], v[74:75] neg_lo:[0,1] neg_hi:[0,1]
	v_pk_mul_f32 v[76:77], v[36:37], v[76:77]
	v_pk_mul_f32 v[78:79], v[38:39], v[78:79]
	v_pk_mul_f32 v[80:81], v[40:41], v[80:81]
	v_pk_mul_f32 v[82:83], v[42:43], v[82:83]
	v_pk_mul_f32 v[84:85], v[44:45], v[84:85]
	v_pk_mul_f32 v[86:87], v[46:47], v[86:87]
	v_pk_mul_f32 v[88:89], v[48:49], v[88:89]
	v_pk_mul_f32 v[90:91], v[50:51], v[90:91]
	v_pk_mul_f32 v[92:93], v[44:45], v[92:93]
	v_pk_mul_f32 v[94:95], v[46:47], v[94:95]
	v_pk_mul_f32 v[96:97], v[48:49], v[96:97]
	v_pk_mul_f32 v[98:99], v[50:51], v[98:99]
	v_cvt_pk_bf16_f32 v52, v68, v69
	v_cvt_pk_bf16_f32 v53, v70, v71
	v_cvt_pk_bf16_f32 v54, v72, v73
	v_cvt_pk_bf16_f32 v55, v74, v75
	v_cvt_pk_bf16_f32 v56, v76, v77
	v_cvt_pk_bf16_f32 v57, v78, v79
	v_cvt_pk_bf16_f32 v58, v80, v81
	v_cvt_pk_bf16_f32 v59, v82, v83
	ds_write_b128 v142, v[52:55]
	ds_write_b128 v142, v[56:59] offset:27648
	v_cvt_pk_bf16_f32 v60, v84, v85
	v_cvt_pk_bf16_f32 v61, v86, v87
	v_cvt_pk_bf16_f32 v62, v88, v89
	v_cvt_pk_bf16_f32 v63, v90, v91
	v_cvt_pk_bf16_f32 v64, v92, v93
	v_cvt_pk_bf16_f32 v65, v94, v95
	v_cvt_pk_bf16_f32 v66, v96, v97
	v_cvt_pk_bf16_f32 v67, v98, v99
	ds_write_b128 v142, v[60:63] offset:9216
	ds_write_b128 v142, v[64:67] offset:18432
	s_and_b64 vcc, exec, s[22:23]
	s_cbranch_vccnz .LBB0_877
	s_cmp_lg_u32 s32, 0
	s_cbranch_scc1 .LBB0_877
	s_mul_hi_i32 s8, s91, 0x3e0f83e1
	s_mov_b64 s[94:95], s[20:21]
	s_mov_b64 s[20:21], s[68:69]
	s_mov_b64 s[68:69], s[66:67]
	s_mov_b64 s[66:67], s[64:65]
	s_mov_b64 s[64:65], s[62:63]
	s_mov_b64 s[62:63], s[18:19]
	s_mov_b64 s[18:19], s[46:47]
	s_mov_b64 s[46:47], s[44:45]
	s_mov_b64 s[44:45], s[42:43]
	s_mov_b64 s[42:43], s[40:41]
	s_mov_b64 s[40:41], s[38:39]
	s_lshr_b32 s9, s8, 31
	s_ashr_i32 s39, s8, 5
	s_add_i32 s39, s39, s9
	s_mul_i32 s8, s39, 0xffffff7c
	s_add_i32 vcc_lo, s90, s8
	s_add_i32 s34, vcc_lo, 1
	s_ashr_i32 s35, s39, 5
	s_and_b32 s38, s39, 1
	s_cmp_eq_u32 s38, 0
	s_cselect_b64 s[84:85], -1, 0
	s_cmp_gt_i32 s34, 3
	s_mov_b64 s[86:87], -1
	s_mul_i32 s8, s39, 0x84
	s_cbranch_scc0 .LBB0_874
	s_add_i32 s9, s27, s8
	s_add_i32 vcc_lo, vcc_lo, -3
	s_and_b64 s[86:87], s[84:85], exec
	s_cselect_b32 s9, vcc_lo, s9
	s_lshl_b32 s86, s35, 13
	s_lshl_b32 s9, s9, 6
	s_add_i32 s9, s9, s86
	s_mov_b64 s[86:87], 0

.LBB0_894:
	s_waitcnt lgkmcnt(0)
	s_barrier
	s_cmp_lg_u32 s32, 0
	s_cbranch_scc0 .Lf1_df_skip0
	s_cmp_ge_u32 s101, 4
	s_cbranch_scc0 .Lf1_df_skip0
	v_lshl_add_u64 v[230:231], v[230:231], 0, s[30:31]
	global_load_dwordx4 v[24:27], v[230:231], off
	v_lshl_add_u64 v[224:225], v[224:225], 0, s[30:31]
	global_load_dwordx4 v[12:15], v[224:225], off
	v_lshl_add_u64 v[226:227], v[226:227], 0, s[30:31]
	global_load_dwordx4 v[16:19], v[226:227], off
	v_lshl_add_u64 v[220:221], v[220:221], 0, s[30:31]
	global_load_dwordx4 v[4:7], v[220:221], off
	v_lshl_add_u64 v[228:229], v[228:229], 0, s[30:31]
	global_load_dwordx4 v[20:23], v[228:229], off
	v_lshl_add_u64 v[222:223], v[222:223], 0, s[30:31]
	global_load_dwordx4 v[8:11], v[222:223], off
.Lf1_df_skip0:
	s_andn2_b64 vcc, exec, s[42:43]
	s_cbranch_vccnz .LBB0_896
	ds_read_b64_tr_b16 v[44:45], v147 offset:64512
	ds_read_b64_tr_b16 v[46:47], v147 offset:65088
	ds_read_b128 v[48:51], v148
	s_waitcnt lgkmcnt(0)
	v_mfma_f32_16x16x32_bf16 v[44:47], v[44:47], v[48:51], 0
	s_nop 7
	v_cvt_pk_bf16_f32 v0, v44, v45
	v_cvt_pk_bf16_f32 v1, v46, v47
	ds_write_b64 v149, v[0:1] offset:46080
	s_waitcnt lgkmcnt(0)
	ds_read_b64_tr_b16 v[44:45], v147 offset:46080
	ds_read_b64_tr_b16 v[46:47], v147 offset:46656
	ds_read_b128 v[48:51], v150 offset:64512
	s_waitcnt lgkmcnt(0)
	v_mfma_f32_16x16x32_bf16 v[44:47], v[44:47], v[48:51], 0
	s_nop 7
	v_cvt_pk_bf16_f32 v0, v44, v45
	v_cvt_pk_bf16_f32 v1, v46, v47
	ds_write_b64 v149, v[0:1] offset:64512
